# MLP-up and PLE-gate GEMMs: unit-head vmcnt(0) moved in front of the unit loop and the first two DMA waits of a unit's first K-loop pass skipped, so the previous unit's epilogue stores drain under the
# speedup vs baseline: 1.0030x; 1.0030x over previous
.LBB0_828:
	s_add_u32 s6, s72, 0x4860000
	s_addc_u32 s7, s73, 0
	s_add_u32 s8, s72, 0xe940000
	s_addc_u32 s9, s73, 0
	s_lshl_b32 s14, s14, 5
	s_and_b32 s22, s14, 0x60
	s_mov_b64 s[14:15], 0x80
	s_add_i32 m0, s54, 0x18000
	v_lshl_add_u64 v[6:7], v[6:7], 0, s[14:15]
	s_lshl_b32 s19, s18, 13
	s_lshl_b32 s23, s22, 7
	s_waitcnt vmcnt(2)
	s_barrier
	global_load_lds_dwordx4 v[6:7], off
	v_lshl_add_u64 v[4:5], v[4:5], 0, s[14:15]
	s_add_i32 m0, s54, 0x1a000
	s_add_i32 s63, s54, 0x8000
	s_add_i32 s64, s54, 0xa000
	global_load_lds_dwordx4 v[4:5], off
	v_lshl_add_u64 v[0:1], v[0:1], 0, s[14:15]
	s_mov_b32 m0, s63
	s_add_u32 s20, s42, 0x40080
	global_load_lds_dwordx4 v[0:1], off
	v_lshl_add_u64 v[0:1], v[2:3], 0, s[14:15]
	s_mov_b32 m0, s64
	s_addc_u32 s21, s43, 0
	global_load_lds_dwordx4 v[0:1], off
	s_add_i32 m0, s54, 0x1c000
	v_lshl_add_u64 v[0:1], s[20:21], 0, v[196:197]
	global_load_lds_dwordx4 v[0:1], off
	v_lshl_add_u64 v[0:1], s[20:21], 0, v[200:201]
	s_add_i32 m0, s54, 0x1e000
	s_sext_i32_i8 s78, s16
	global_load_lds_dwordx4 v[0:1], off
	v_and_b32_e32 v0, 15, v192
	v_lshlrev_b32_e32 v1, 1, v11
	v_lshlrev_b32_e32 v2, 2, v192
	v_lshlrev_b32_e32 v3, 6, v192
	s_movk_i32 s16, 0x3c0
	v_lshl_or_b32 v193, s18, 6, v0
	v_lshl_or_b32 v0, v0, 6, v1
	v_and_b32_e32 v2, 32, v2
	v_and_or_b32 v1, v3, s16, v1
	v_bitop3_b32 v220, s23, v1, v2 bitop3:0xf6
	v_lshlrev_b32_e32 v1, 8, v192
	v_bitop3_b32 v0, v0, s19, v2 bitop3:0xde
	v_and_b32_e32 v1, 0x38000, v1
	v_lshlrev_b32_e32 v2, 11, v10
	v_or3_b32 v1, v8, v1, v2
	v_add_u32_e32 v202, v1, v9
	v_lshlrev_b32_e32 v1, 4, v12
	s_waitcnt vmcnt(6)
	v_and_b32_e32 v1, 0x78000, v1
	s_cmpk_lt_u32 s17, 0x100
	v_or3_b32 v1, v8, v1, v2
	s_cselect_b64 s[16:17], -1, 0
	s_ashr_i32 s65, s34, 31
	s_mov_b32 s66, s34
	v_or_b32_e32 v221, s22, v11
	v_mov_b32_e32 v203, v197
	v_add_u32_e32 v204, v1, v9
	v_mov_b32_e32 v205, v197
	v_mov_b32_e32 v222, 0x358637bd
	s_mov_b32 s67, 0x800000
	s_mov_b64 s[18:19], 0x100000
	s_mov_b32 s68, 0x100000
	s_mov_b64 s[20:21], 0x120000
	s_mov_b32 s69, 0x120000
	s_mov_b64 s[22:23], 0x140000
	s_mov_b32 s76, 0x140000
	s_mov_b64 s[24:25], 0x160000
	s_mov_b32 s77, 0x160000
	v_mov_b64_e32 v[206:207], 0x7ff
	v_add_u32_e32 v223, 0, v0
	s_barrier
	s_waitcnt vmcnt(0)
	s_branch .LBB0_831

.LBB0_838:
	s_ashr_i32 s29, s28, 31
	s_lshl_b64 s[30:31], s[28:29], 19
	s_add_u32 s30, s12, s30
	s_addc_u32 s31, s13, s31
	s_and_b64 s[38:39], s[36:37], exec
	s_cselect_b32 s29, s31, s45
	s_cselect_b32 s79, s30, s44
	s_ashr_i32 s27, s26, 31
	s_lshl_b64 s[38:39], s[26:27], 19
	s_add_u32 s38, s51, s38
	s_addc_u32 s39, s52, s39
	s_and_b64 s[46:47], s[36:37], exec
	s_cselect_b32 s27, s39, s43
	s_cselect_b32 s80, s38, s42
	v_lshl_add_u32 v208, s40, 8, v193
	s_add_u32 s40, s44, 0x40080
	s_addc_u32 s41, s45, 0
	v_ashrrev_i32_e32 v209, 31, v208
	s_add_u32 s81, s42, 0x100
	v_mov_b32_e32 v0, 0
	v_lshl_add_u64 v[210:211], v[208:209], 2, s[6:7]
	s_addc_u32 s82, s43, 0
	s_mov_b32 s83, -2
	v_mov_b32_e32 v1, v0
	v_mov_b32_e32 v2, v0
	v_mov_b32_e32 v3, v0
	v_mov_b32_e32 v4, v0
	v_mov_b32_e32 v5, v0
	v_mov_b32_e32 v6, v0
	v_mov_b32_e32 v7, v0
	v_mov_b32_e32 v16, v0
	v_mov_b32_e32 v17, v0
	v_mov_b32_e32 v18, v0
	v_mov_b32_e32 v19, v0
	v_mov_b32_e32 v20, v0
	v_mov_b32_e32 v21, v0
	v_mov_b32_e32 v22, v0
	v_mov_b32_e32 v23, v0
	v_mov_b32_e32 v32, v0
	v_mov_b32_e32 v33, v0
	v_mov_b32_e32 v34, v0
	v_mov_b32_e32 v35, v0
	v_mov_b32_e32 v36, v0
	v_mov_b32_e32 v37, v0
	v_mov_b32_e32 v38, v0
	v_mov_b32_e32 v39, v0
	v_mov_b32_e32 v48, v0
	v_mov_b32_e32 v49, v0
	v_mov_b32_e32 v50, v0
	v_mov_b32_e32 v51, v0
	v_mov_b32_e32 v52, v0
	v_mov_b32_e32 v53, v0
	v_mov_b32_e32 v54, v0
	v_mov_b32_e32 v55, v0
	v_mov_b32_e32 v8, v0
	v_mov_b32_e32 v9, v0
	v_mov_b32_e32 v10, v0
	v_mov_b32_e32 v11, v0
	v_mov_b32_e32 v12, v0
	v_mov_b32_e32 v13, v0
	v_mov_b32_e32 v14, v0
	v_mov_b32_e32 v15, v0
	v_mov_b32_e32 v24, v0
	v_mov_b32_e32 v25, v0
	v_mov_b32_e32 v26, v0
	v_mov_b32_e32 v27, v0
	v_mov_b32_e32 v28, v0
	v_mov_b32_e32 v29, v0
	v_mov_b32_e32 v30, v0
	v_mov_b32_e32 v31, v0
	v_mov_b32_e32 v40, v0
	v_mov_b32_e32 v41, v0
	v_mov_b32_e32 v42, v0
	v_mov_b32_e32 v43, v0
	v_mov_b32_e32 v44, v0
	v_mov_b32_e32 v45, v0
	v_mov_b32_e32 v46, v0
	v_mov_b32_e32 v47, v0
	v_mov_b32_e32 v56, v0
	v_mov_b32_e32 v57, v0
	v_mov_b32_e32 v58, v0
	v_mov_b32_e32 v59, v0
	v_mov_b32_e32 v60, v0
	v_mov_b32_e32 v61, v0
	v_mov_b32_e32 v62, v0
	v_mov_b32_e32 v63, v0
	v_mov_b32_e32 v64, v0
	v_mov_b32_e32 v65, v0
	v_mov_b32_e32 v66, v0
	v_mov_b32_e32 v67, v0
	v_mov_b32_e32 v68, v0
	v_mov_b32_e32 v69, v0
	v_mov_b32_e32 v70, v0
	v_mov_b32_e32 v71, v0
	v_mov_b32_e32 v80, v0
	v_mov_b32_e32 v81, v0
	v_mov_b32_e32 v82, v0
	v_mov_b32_e32 v83, v0
	v_mov_b32_e32 v84, v0
	v_mov_b32_e32 v85, v0
	v_mov_b32_e32 v86, v0
	v_mov_b32_e32 v87, v0
	v_mov_b32_e32 v96, v0
	v_mov_b32_e32 v97, v0
	v_mov_b32_e32 v98, v0
	v_mov_b32_e32 v99, v0
	v_mov_b32_e32 v100, v0
	v_mov_b32_e32 v101, v0
	v_mov_b32_e32 v102, v0
	v_mov_b32_e32 v103, v0
	v_mov_b32_e32 v112, v0
	v_mov_b32_e32 v113, v0
	v_mov_b32_e32 v114, v0
	v_mov_b32_e32 v115, v0
	v_mov_b32_e32 v116, v0
	v_mov_b32_e32 v117, v0
	v_mov_b32_e32 v118, v0
	v_mov_b32_e32 v119, v0
	v_mov_b32_e32 v72, v0
	v_mov_b32_e32 v73, v0
	v_mov_b32_e32 v74, v0
	v_mov_b32_e32 v75, v0
	v_mov_b32_e32 v76, v0
	v_mov_b32_e32 v77, v0
	v_mov_b32_e32 v78, v0
	v_mov_b32_e32 v79, v0
	v_mov_b32_e32 v88, v0
	v_mov_b32_e32 v89, v0
	v_mov_b32_e32 v90, v0
	v_mov_b32_e32 v91, v0
	v_mov_b32_e32 v92, v0
	v_mov_b32_e32 v93, v0
	v_mov_b32_e32 v94, v0
	v_mov_b32_e32 v95, v0
	v_mov_b32_e32 v104, v0
	v_mov_b32_e32 v105, v0
	v_mov_b32_e32 v106, v0
	v_mov_b32_e32 v107, v0
	v_mov_b32_e32 v108, v0
	v_mov_b32_e32 v109, v0
	v_mov_b32_e32 v110, v0
	v_mov_b32_e32 v111, v0
	v_mov_b32_e32 v120, v0
	v_mov_b32_e32 v121, v0
	v_mov_b32_e32 v122, v0
	v_mov_b32_e32 v123, v0
	v_mov_b32_e32 v124, v0
	v_mov_b32_e32 v125, v0
	v_mov_b32_e32 v126, v0
	v_mov_b32_e32 v127, v0
	s_branch .LBB0_840

.LBB0_842:
	v_add_u32_e32 v128, 0, v220
	v_add_u32_e32 v129, 0x10000, v128
	v_add_u32_e32 v140, 0x14000, v128
	ds_read_b128 v[144:147], v129
	ds_read_b128 v[148:151], v129 offset:1024
	ds_read_b128 v[152:155], v129 offset:2048
	ds_read_b128 v[156:159], v129 offset:3072
	ds_read_b128 v[128:131], v140
	ds_read_b128 v[132:135], v140 offset:1024
	ds_read_b128 v[136:139], v140 offset:2048
	ds_read_b128 v[140:143], v140 offset:3072
	v_lshl_add_u64 v[212:213], s[40:41], 0, v[202:203]
	s_add_i32 m0, s54, 0xc000
	ds_read_b128 v[184:187], v223
	ds_read_b128 v[188:191], v223 offset:1024
	ds_read_b128 v[176:179], v223 offset:2048
	ds_read_b128 v[180:183], v223 offset:3072
	ds_read_b128 v[168:171], v223 offset:4096
	ds_read_b128 v[172:175], v223 offset:5120
	ds_read_b128 v[160:163], v223 offset:6144
	ds_read_b128 v[164:167], v223 offset:7168
	global_load_lds_dwordx4 v[212:213], off
	v_lshl_add_u64 v[212:213], s[40:41], 0, v[204:205]
	s_add_i32 m0, s54, 0xe000
	s_mov_b64 s[46:47], -1
	global_load_lds_dwordx4 v[212:213], off
	s_cmp_eq_i32 s83, -2
	s_cbranch_scc1 .LBB0_846
	s_and_b64 vcc, exec, s[44:45]
	s_cbranch_vccz .LBB0_844
	s_waitcnt vmcnt(8)
	s_mov_b64 s[46:47], 0

.LBB0_846:
	s_add_u32 s46, s40, 0xfffc0080
	s_addc_u32 s47, s41, -1
	s_waitcnt lgkmcnt(0)
	s_and_b64 s[42:43], s[42:43], exec
	s_cselect_b32 s47, s29, s47
	s_cselect_b32 s46, s79, s46
	s_cselect_b32 s43, s27, s82
	s_cselect_b32 s42, s80, s81
	s_barrier
	s_waitcnt lgkmcnt(0)
	v_mfma_f32_16x16x32_bf16 v[124:127], v[144:147], v[184:187], v[124:127]
	v_mfma_f32_16x16x32_bf16 v[120:123], v[152:155], v[184:187], v[120:123]
	v_mfma_f32_16x16x32_bf16 v[108:111], v[144:147], v[176:179], v[108:111]
	v_mfma_f32_16x16x32_bf16 v[104:107], v[152:155], v[176:179], v[104:107]
	v_mfma_f32_16x16x32_bf16 v[92:95], v[144:147], v[168:171], v[92:95]
	v_mfma_f32_16x16x32_bf16 v[88:91], v[152:155], v[168:171], v[88:91]
	v_mfma_f32_16x16x32_bf16 v[76:79], v[144:147], v[160:163], v[76:79]
	v_mfma_f32_16x16x32_bf16 v[72:75], v[152:155], v[160:163], v[72:75]
	v_mfma_f32_16x16x32_bf16 v[124:127], v[148:151], v[188:191], v[124:127]
	v_mfma_f32_16x16x32_bf16 v[120:123], v[156:159], v[188:191], v[120:123]
	v_mfma_f32_16x16x32_bf16 v[108:111], v[148:151], v[180:183], v[108:111]
	v_mfma_f32_16x16x32_bf16 v[104:107], v[156:159], v[180:183], v[104:107]
	v_mfma_f32_16x16x32_bf16 v[92:95], v[148:151], v[172:175], v[92:95]
	v_mfma_f32_16x16x32_bf16 v[88:91], v[156:159], v[172:175], v[88:91]
	v_mfma_f32_16x16x32_bf16 v[76:79], v[148:151], v[164:167], v[76:79]
	v_mfma_f32_16x16x32_bf16 v[72:75], v[156:159], v[164:167], v[72:75]
	v_mfma_f32_16x16x32_bf16 v[116:119], v[128:131], v[184:187], v[116:119]
	v_mfma_f32_16x16x32_bf16 v[112:115], v[136:139], v[184:187], v[112:115]
	v_mfma_f32_16x16x32_bf16 v[100:103], v[128:131], v[176:179], v[100:103]
	v_mfma_f32_16x16x32_bf16 v[96:99], v[136:139], v[176:179], v[96:99]
	v_mfma_f32_16x16x32_bf16 v[84:87], v[128:131], v[168:171], v[84:87]
	v_mfma_f32_16x16x32_bf16 v[80:83], v[136:139], v[168:171], v[80:83]
	v_mfma_f32_16x16x32_bf16 v[68:71], v[128:131], v[160:163], v[68:71]
	v_mfma_f32_16x16x32_bf16 v[64:67], v[136:139], v[160:163], v[64:67]
	v_mfma_f32_16x16x32_bf16 v[116:119], v[132:135], v[188:191], v[116:119]
	v_mfma_f32_16x16x32_bf16 v[112:115], v[140:143], v[188:191], v[112:115]
	v_mfma_f32_16x16x32_bf16 v[100:103], v[132:135], v[180:183], v[100:103]
	v_mfma_f32_16x16x32_bf16 v[96:99], v[140:143], v[180:183], v[96:99]
	v_mfma_f32_16x16x32_bf16 v[84:87], v[132:135], v[172:175], v[84:87]
	v_mfma_f32_16x16x32_bf16 v[80:83], v[140:143], v[172:175], v[80:83]
	v_mfma_f32_16x16x32_bf16 v[68:71], v[132:135], v[164:167], v[68:71]
	v_mfma_f32_16x16x32_bf16 v[64:67], v[140:143], v[164:167], v[64:67]
	s_barrier
	s_mov_b32 m0, s55
	v_lshl_add_u64 v[218:219], s[42:43], 0, v[196:197]
	s_add_u32 s48, s42, 0x40000
	ds_read_b128 v[184:187], v223 offset:16384
	ds_read_b128 v[188:191], v223 offset:17408
	ds_read_b128 v[176:179], v223 offset:18432
	ds_read_b128 v[180:183], v223 offset:19456
	ds_read_b128 v[168:171], v223 offset:20480
	ds_read_b128 v[172:175], v223 offset:21504
	ds_read_b128 v[160:163], v223 offset:22528
	ds_read_b128 v[164:167], v223 offset:23552
	global_load_lds_dwordx4 v[218:219], off
	v_lshl_add_u64 v[216:217], s[42:43], 0, v[200:201]
	s_mov_b32 m0, s56
	s_addc_u32 s49, s43, 0
	global_load_lds_dwordx4 v[216:217], off
	v_lshl_add_u64 v[212:213], s[48:49], 0, v[196:197]
	s_mov_b32 m0, s57
	v_lshl_add_u64 v[214:215], s[46:47], 0, v[198:199]
	global_load_lds_dwordx4 v[212:213], off
	v_lshl_add_u64 v[212:213], s[48:49], 0, v[200:201]
	s_mov_b32 m0, s58
	s_mov_b64 s[48:49], -1
	global_load_lds_dwordx4 v[212:213], off
	v_lshl_add_u64 v[212:213], s[46:47], 0, v[194:195]
	s_mov_b32 m0, s54
	s_and_b64 vcc, exec, s[44:45]
	global_load_lds_dwordx4 v[212:213], off
	s_mov_b32 m0, s59
	s_nop 0
	global_load_lds_dwordx4 v[214:215], off
	s_cmp_eq_i32 s83, -2
	s_cbranch_scc1 .LBB0_839
	s_cbranch_vccz .LBB0_848
	s_waitcnt vmcnt(8)
	s_mov_b64 s[48:49], 0

.LBB0_1052:
	s_add_u32 s8, s72, 0x4880000
	s_addc_u32 s9, s73, 0
	s_add_u32 s16, s72, 0x48a0000
	s_addc_u32 s17, s73, 0
	s_lshl_b32 s5, s5, 5
	s_mov_b64 s[18:19], 0x80
	s_and_b32 s24, s5, 0x60
	s_add_i32 m0, s51, 0x18000
	v_lshl_add_u64 v[6:7], v[6:7], 0, s[18:19]
	s_lshl_b32 s21, s4, 13
	s_lshl_b32 s5, s24, 7
	s_waitcnt vmcnt(2)
	s_barrier
	global_load_lds_dwordx4 v[6:7], off
	v_lshl_add_u64 v[4:5], v[4:5], 0, s[18:19]
	s_add_i32 m0, s51, 0x1a000
	s_add_i32 s60, s51, 0x8000
	s_add_i32 s61, s51, 0xa000
	global_load_lds_dwordx4 v[4:5], off
	v_lshl_add_u64 v[0:1], v[0:1], 0, s[18:19]
	s_mov_b32 m0, s60
	s_add_u32 s22, s40, 0x40080
	global_load_lds_dwordx4 v[0:1], off
	v_lshl_add_u64 v[0:1], v[2:3], 0, s[18:19]
	s_mov_b32 m0, s61
	s_addc_u32 s23, s41, 0
	global_load_lds_dwordx4 v[0:1], off
	s_add_i32 m0, s51, 0x1c000
	v_lshl_add_u64 v[0:1], s[22:23], 0, v[196:197]
	global_load_lds_dwordx4 v[0:1], off
	v_lshl_add_u64 v[0:1], s[22:23], 0, v[200:201]
	s_add_i32 m0, s51, 0x1e000
	v_lshlrev_b32_e32 v3, 2, v192
	global_load_lds_dwordx4 v[0:1], off
	v_and_b32_e32 v0, 15, v192
	v_bfe_u32 v1, v192, 4, 2
	v_lshl_or_b32 v193, s4, 6, v0
	v_lshlrev_b32_e32 v2, 4, v1
	v_lshlrev_b32_e32 v4, 6, v192
	s_movk_i32 s4, 0x3c0
	v_lshl_or_b32 v0, v0, 6, v2
	v_and_b32_e32 v3, 32, v3
	v_and_or_b32 v2, v4, s4, v2
	v_bitop3_b32 v220, s5, v2, v3 bitop3:0xf6
	v_cmp_eq_u32_e64 s[4:5], 0, v1
	v_lshl_or_b32 v221, v1, 3, s24
	v_lshlrev_b32_e32 v1, 8, v192
	v_and_b32_e32 v1, 0x38000, v1
	v_lshlrev_b32_e32 v2, 11, v10
	v_or3_b32 v1, v8, v1, v2
	v_add_u32_e32 v202, v1, v9
	v_lshlrev_b32_e32 v1, 4, v11
	v_and_b32_e32 v1, 0x78000, v1
	s_waitcnt vmcnt(6)
	v_or3_b32 v1, v8, v1, v2
	v_bitop3_b32 v0, v0, s21, v3 bitop3:0xde
	s_cmpk_lt_u32 s20, 0x100
	v_add_u32_e32 v204, v1, v9
	v_mbcnt_lo_u32_b32 v1, -1, 0
	s_cselect_b64 s[20:21], -1, 0
	s_ashr_i32 s62, s34, 31
	s_mov_b32 s63, s34
	s_ashr_i32 s64, s2, 31
	v_mov_b32_e32 v203, v197
	v_mov_b32_e32 v205, v197
	v_mov_b32_e32 v222, 0x358637bd
	s_mov_b32 s65, 0x800000
	v_mbcnt_hi_u32_b32 v223, -1, v1
	v_mov_b64_e32 v[206:207], 0x1ff
	v_add_u32_e32 v224, 0, v0
	s_barrier
	s_waitcnt vmcnt(0)
	s_branch .LBB0_1055

.LBB0_1062:
	s_ashr_i32 s25, s24, 31
	s_lshl_b64 s[26:27], s[24:25], 19
	s_add_u32 s26, s12, s26
	s_addc_u32 s27, s13, s27
	s_and_b64 s[30:31], s[28:29], exec
	s_cselect_b32 s25, s27, s43
	s_cselect_b32 s37, s26, s42
	s_ashr_i32 s23, s22, 31
	s_lshl_b64 s[30:31], s[22:23], 19
	s_add_u32 s30, s48, s30
	s_addc_u32 s31, s49, s31
	s_and_b64 s[44:45], s[28:29], exec
	s_cselect_b32 s23, s31, s41
	s_cselect_b32 s66, s30, s40
	v_lshl_add_u32 v208, s38, 8, v193
	s_add_u32 s38, s42, 0x40080
	s_addc_u32 s39, s43, 0
	v_ashrrev_i32_e32 v209, 31, v208
	s_add_u32 s67, s40, 0x100
	v_mov_b32_e32 v0, 0
	v_lshl_add_u64 v[210:211], v[208:209], 2, s[8:9]
	s_addc_u32 s68, s41, 0
	s_mov_b32 s69, -2
	s_waitcnt lgkmcnt(0)
	v_mov_b32_e32 v1, v0
	v_mov_b32_e32 v2, v0
	v_mov_b32_e32 v3, v0
	v_mov_b32_e32 v4, v0
	v_mov_b32_e32 v5, v0
	v_mov_b32_e32 v6, v0
	v_mov_b32_e32 v7, v0
	v_mov_b32_e32 v16, v0
	v_mov_b32_e32 v17, v0
	v_mov_b32_e32 v18, v0
	v_mov_b32_e32 v19, v0
	v_mov_b32_e32 v20, v0
	v_mov_b32_e32 v21, v0
	v_mov_b32_e32 v22, v0
	v_mov_b32_e32 v23, v0
	v_mov_b32_e32 v32, v0
	v_mov_b32_e32 v33, v0
	v_mov_b32_e32 v34, v0
	v_mov_b32_e32 v35, v0
	v_mov_b32_e32 v36, v0
	v_mov_b32_e32 v37, v0
	v_mov_b32_e32 v38, v0
	v_mov_b32_e32 v39, v0
	v_mov_b32_e32 v48, v0
	v_mov_b32_e32 v49, v0
	v_mov_b32_e32 v50, v0
	v_mov_b32_e32 v51, v0
	v_mov_b32_e32 v52, v0
	v_mov_b32_e32 v53, v0
	v_mov_b32_e32 v54, v0
	v_mov_b32_e32 v55, v0
	v_mov_b32_e32 v8, v0
	v_mov_b32_e32 v9, v0
	v_mov_b32_e32 v10, v0
	v_mov_b32_e32 v11, v0
	v_mov_b32_e32 v12, v0
	v_mov_b32_e32 v13, v0
	v_mov_b32_e32 v14, v0
	v_mov_b32_e32 v15, v0
	v_mov_b32_e32 v24, v0
	v_mov_b32_e32 v25, v0
	v_mov_b32_e32 v26, v0
	v_mov_b32_e32 v27, v0
	v_mov_b32_e32 v28, v0
	v_mov_b32_e32 v29, v0
	v_mov_b32_e32 v30, v0
	v_mov_b32_e32 v31, v0
	v_mov_b32_e32 v40, v0
	v_mov_b32_e32 v41, v0
	v_mov_b32_e32 v42, v0
	v_mov_b32_e32 v43, v0
	v_mov_b32_e32 v44, v0
	v_mov_b32_e32 v45, v0
	v_mov_b32_e32 v46, v0
	v_mov_b32_e32 v47, v0
	v_mov_b32_e32 v56, v0
	v_mov_b32_e32 v57, v0
	v_mov_b32_e32 v58, v0
	v_mov_b32_e32 v59, v0
	v_mov_b32_e32 v60, v0
	v_mov_b32_e32 v61, v0
	v_mov_b32_e32 v62, v0
	v_mov_b32_e32 v63, v0
	v_mov_b32_e32 v64, v0
	v_mov_b32_e32 v65, v0
	v_mov_b32_e32 v66, v0
	v_mov_b32_e32 v67, v0
	v_mov_b32_e32 v68, v0
	v_mov_b32_e32 v69, v0
	v_mov_b32_e32 v70, v0
	v_mov_b32_e32 v71, v0
	v_mov_b32_e32 v80, v0
	v_mov_b32_e32 v81, v0
	v_mov_b32_e32 v82, v0
	v_mov_b32_e32 v83, v0
	v_mov_b32_e32 v84, v0
	v_mov_b32_e32 v85, v0
	v_mov_b32_e32 v86, v0
	v_mov_b32_e32 v87, v0
	v_mov_b32_e32 v96, v0
	v_mov_b32_e32 v97, v0
	v_mov_b32_e32 v98, v0
	v_mov_b32_e32 v99, v0
	v_mov_b32_e32 v100, v0
	v_mov_b32_e32 v101, v0
	v_mov_b32_e32 v102, v0
	v_mov_b32_e32 v103, v0
	v_mov_b32_e32 v112, v0
	v_mov_b32_e32 v113, v0
	v_mov_b32_e32 v114, v0
	v_mov_b32_e32 v115, v0
	v_mov_b32_e32 v116, v0
	v_mov_b32_e32 v117, v0
	v_mov_b32_e32 v118, v0
	v_mov_b32_e32 v119, v0
	v_mov_b32_e32 v72, v0
	v_mov_b32_e32 v73, v0
	v_mov_b32_e32 v74, v0
	v_mov_b32_e32 v75, v0
	v_mov_b32_e32 v76, v0
	v_mov_b32_e32 v77, v0
	v_mov_b32_e32 v78, v0
	v_mov_b32_e32 v79, v0
	v_mov_b32_e32 v88, v0
	v_mov_b32_e32 v89, v0
	v_mov_b32_e32 v90, v0
	v_mov_b32_e32 v91, v0
	v_mov_b32_e32 v92, v0
	v_mov_b32_e32 v93, v0
	v_mov_b32_e32 v94, v0
	v_mov_b32_e32 v95, v0
	v_mov_b32_e32 v104, v0
	v_mov_b32_e32 v105, v0
	v_mov_b32_e32 v106, v0
	v_mov_b32_e32 v107, v0
	v_mov_b32_e32 v108, v0
	v_mov_b32_e32 v109, v0
	v_mov_b32_e32 v110, v0
	v_mov_b32_e32 v111, v0
	v_mov_b32_e32 v120, v0
	v_mov_b32_e32 v121, v0
	v_mov_b32_e32 v122, v0
	v_mov_b32_e32 v123, v0
	v_mov_b32_e32 v128, v0
	v_mov_b32_e32 v129, v0
	v_mov_b32_e32 v130, v0
	v_mov_b32_e32 v131, v0
	s_branch .LBB0_1064

.LBB0_1066:
	v_add_u32_e32 v124, 0, v220
	v_add_u32_e32 v125, 0x10000, v124
	v_add_u32_e32 v140, 0x14000, v124
	ds_read_b128 v[144:147], v125
	ds_read_b128 v[148:151], v125 offset:1024
	ds_read_b128 v[152:155], v125 offset:2048
	ds_read_b128 v[156:159], v125 offset:3072
	ds_read_b128 v[124:127], v140
	ds_read_b128 v[132:135], v140 offset:1024
	ds_read_b128 v[136:139], v140 offset:2048
	ds_read_b128 v[140:143], v140 offset:3072
	v_lshl_add_u64 v[212:213], s[38:39], 0, v[202:203]
	s_add_i32 m0, s51, 0xc000
	ds_read_b128 v[184:187], v224
	ds_read_b128 v[188:191], v224 offset:1024
	ds_read_b128 v[176:179], v224 offset:2048
	ds_read_b128 v[180:183], v224 offset:3072
	ds_read_b128 v[168:171], v224 offset:4096
	ds_read_b128 v[172:175], v224 offset:5120
	ds_read_b128 v[160:163], v224 offset:6144
	ds_read_b128 v[164:167], v224 offset:7168
	global_load_lds_dwordx4 v[212:213], off
	v_lshl_add_u64 v[212:213], s[38:39], 0, v[204:205]
	s_add_i32 m0, s51, 0xe000
	s_mov_b64 s[44:45], -1
	global_load_lds_dwordx4 v[212:213], off
	s_cmp_eq_i32 s69, -2
	s_cbranch_scc1 .LBB0_1070
	s_and_b64 vcc, exec, s[42:43]
	s_cbranch_vccz .LBB0_1068
	s_waitcnt vmcnt(8)
	s_mov_b64 s[44:45], 0

.LBB0_1070:
	s_add_u32 s44, s38, 0xfffc0080
	s_addc_u32 s45, s39, -1
	s_waitcnt lgkmcnt(0)
	s_and_b64 s[40:41], s[40:41], exec
	s_cselect_b32 s45, s25, s45
	s_cselect_b32 s44, s37, s44
	s_cselect_b32 s41, s23, s68
	s_cselect_b32 s40, s66, s67
	s_barrier
	s_waitcnt lgkmcnt(0)
	v_mfma_f32_16x16x32_bf16 v[128:131], v[144:147], v[184:187], v[128:131]
	v_mfma_f32_16x16x32_bf16 v[120:123], v[152:155], v[184:187], v[120:123]
	v_mfma_f32_16x16x32_bf16 v[108:111], v[144:147], v[176:179], v[108:111]
	v_mfma_f32_16x16x32_bf16 v[104:107], v[152:155], v[176:179], v[104:107]
	v_mfma_f32_16x16x32_bf16 v[92:95], v[144:147], v[168:171], v[92:95]
	v_mfma_f32_16x16x32_bf16 v[88:91], v[152:155], v[168:171], v[88:91]
	v_mfma_f32_16x16x32_bf16 v[76:79], v[144:147], v[160:163], v[76:79]
	v_mfma_f32_16x16x32_bf16 v[72:75], v[152:155], v[160:163], v[72:75]
	v_mfma_f32_16x16x32_bf16 v[128:131], v[148:151], v[188:191], v[128:131]
	v_mfma_f32_16x16x32_bf16 v[120:123], v[156:159], v[188:191], v[120:123]
	v_mfma_f32_16x16x32_bf16 v[108:111], v[148:151], v[180:183], v[108:111]
	v_mfma_f32_16x16x32_bf16 v[104:107], v[156:159], v[180:183], v[104:107]
	v_mfma_f32_16x16x32_bf16 v[92:95], v[148:151], v[172:175], v[92:95]
	v_mfma_f32_16x16x32_bf16 v[88:91], v[156:159], v[172:175], v[88:91]
	v_mfma_f32_16x16x32_bf16 v[76:79], v[148:151], v[164:167], v[76:79]
	v_mfma_f32_16x16x32_bf16 v[72:75], v[156:159], v[164:167], v[72:75]
	v_mfma_f32_16x16x32_bf16 v[116:119], v[124:127], v[184:187], v[116:119]
	v_mfma_f32_16x16x32_bf16 v[112:115], v[136:139], v[184:187], v[112:115]
	v_mfma_f32_16x16x32_bf16 v[100:103], v[124:127], v[176:179], v[100:103]
	v_mfma_f32_16x16x32_bf16 v[96:99], v[136:139], v[176:179], v[96:99]
	v_mfma_f32_16x16x32_bf16 v[84:87], v[124:127], v[168:171], v[84:87]
	v_mfma_f32_16x16x32_bf16 v[80:83], v[136:139], v[168:171], v[80:83]
	v_mfma_f32_16x16x32_bf16 v[68:71], v[124:127], v[160:163], v[68:71]
	v_mfma_f32_16x16x32_bf16 v[64:67], v[136:139], v[160:163], v[64:67]
	v_mfma_f32_16x16x32_bf16 v[116:119], v[132:135], v[188:191], v[116:119]
	v_mfma_f32_16x16x32_bf16 v[112:115], v[140:143], v[188:191], v[112:115]
	v_mfma_f32_16x16x32_bf16 v[100:103], v[132:135], v[180:183], v[100:103]
	v_mfma_f32_16x16x32_bf16 v[96:99], v[140:143], v[180:183], v[96:99]
	v_mfma_f32_16x16x32_bf16 v[84:87], v[132:135], v[172:175], v[84:87]
	v_mfma_f32_16x16x32_bf16 v[80:83], v[140:143], v[172:175], v[80:83]
	v_mfma_f32_16x16x32_bf16 v[68:71], v[132:135], v[164:167], v[68:71]
	v_mfma_f32_16x16x32_bf16 v[64:67], v[140:143], v[164:167], v[64:67]
	s_barrier
	s_mov_b32 m0, s52
	v_lshl_add_u64 v[218:219], s[40:41], 0, v[196:197]
	s_add_u32 s46, s40, 0x40000
	ds_read_b128 v[184:187], v224 offset:16384
	ds_read_b128 v[188:191], v224 offset:17408
	ds_read_b128 v[176:179], v224 offset:18432
	ds_read_b128 v[180:183], v224 offset:19456
	ds_read_b128 v[168:171], v224 offset:20480
	ds_read_b128 v[172:175], v224 offset:21504
	ds_read_b128 v[160:163], v224 offset:22528
	ds_read_b128 v[164:167], v224 offset:23552
	global_load_lds_dwordx4 v[218:219], off
	v_lshl_add_u64 v[216:217], s[40:41], 0, v[200:201]
	s_mov_b32 m0, s53
	s_addc_u32 s47, s41, 0
	global_load_lds_dwordx4 v[216:217], off
	v_lshl_add_u64 v[212:213], s[46:47], 0, v[196:197]
	s_mov_b32 m0, s54
	v_lshl_add_u64 v[214:215], s[44:45], 0, v[198:199]
	global_load_lds_dwordx4 v[212:213], off
	v_lshl_add_u64 v[212:213], s[46:47], 0, v[200:201]
	s_mov_b32 m0, s55
	s_mov_b64 s[46:47], -1
	global_load_lds_dwordx4 v[212:213], off
	v_lshl_add_u64 v[212:213], s[44:45], 0, v[194:195]
	s_mov_b32 m0, s51
	s_and_b64 vcc, exec, s[42:43]
	global_load_lds_dwordx4 v[212:213], off
	s_mov_b32 m0, s56
	s_nop 0
	global_load_lds_dwordx4 v[214:215], off
	s_cmp_eq_i32 s69, -2
	s_cbranch_scc1 .LBB0_1063
	s_cbranch_vccz .LBB0_1072
	s_waitcnt vmcnt(8)
	s_mov_b64 s[46:47], 0

.LBB0_1274:
	s_add_u32 s6, s72, 0x48c0000
	s_addc_u32 s7, s73, 0
	s_add_u32 s8, s72, 0xe940000
	s_addc_u32 s9, s73, 0
	s_lshl_b32 s16, s16, 5
	s_and_b32 s24, s16, 0x60
	s_mov_b64 s[16:17], 0x80
	s_add_i32 m0, s56, 0x18000
	v_lshl_add_u64 v[6:7], v[6:7], 0, s[16:17]
	s_lshl_b32 s21, s20, 13
	s_lshl_b32 s25, s24, 7
	s_waitcnt vmcnt(2)
	s_barrier
	global_load_lds_dwordx4 v[6:7], off
	v_lshl_add_u64 v[4:5], v[4:5], 0, s[16:17]
	s_add_i32 m0, s56, 0x1a000
	s_add_i32 s65, s56, 0x8000
	s_add_i32 s66, s56, 0xa000
	global_load_lds_dwordx4 v[4:5], off
	v_lshl_add_u64 v[0:1], v[0:1], 0, s[16:17]
	s_mov_b32 m0, s65
	s_add_u32 s22, s44, 0x40080
	global_load_lds_dwordx4 v[0:1], off
	v_lshl_add_u64 v[0:1], v[2:3], 0, s[16:17]
	s_mov_b32 m0, s66
	s_addc_u32 s23, s45, 0
	global_load_lds_dwordx4 v[0:1], off
	s_add_i32 m0, s56, 0x1c000
	v_lshl_add_u64 v[0:1], s[22:23], 0, v[196:197]
	global_load_lds_dwordx4 v[0:1], off
	v_lshl_add_u64 v[0:1], s[22:23], 0, v[200:201]
	s_add_i32 m0, s56, 0x1e000
	s_sext_i32_i8 s80, s18
	global_load_lds_dwordx4 v[0:1], off
	v_and_b32_e32 v0, 15, v192
	v_lshlrev_b32_e32 v1, 1, v11
	v_lshlrev_b32_e32 v2, 2, v192
	v_lshlrev_b32_e32 v3, 6, v192
	s_movk_i32 s18, 0x3c0
	v_lshl_or_b32 v193, s20, 6, v0
	v_lshl_or_b32 v0, v0, 6, v1
	v_and_b32_e32 v2, 32, v2
	v_and_or_b32 v1, v3, s18, v1
	v_bitop3_b32 v220, s25, v1, v2 bitop3:0xf6
	v_lshlrev_b32_e32 v1, 8, v192
	v_bitop3_b32 v0, v0, s21, v2 bitop3:0xde
	v_and_b32_e32 v1, 0x38000, v1
	v_lshlrev_b32_e32 v2, 11, v10
	v_or3_b32 v1, v8, v1, v2
	v_add_u32_e32 v202, v1, v9
	v_lshlrev_b32_e32 v1, 4, v12
	s_waitcnt vmcnt(6)
	v_and_b32_e32 v1, 0x78000, v1
	s_cmpk_lt_u32 s19, 0x100
	v_or3_b32 v1, v8, v1, v2
	s_cselect_b64 s[18:19], -1, 0
	s_ashr_i32 s67, s34, 31
	s_mov_b32 s68, s34
	v_or_b32_e32 v221, s24, v11
	v_mov_b32_e32 v203, v197
	v_add_u32_e32 v204, v1, v9
	v_mov_b32_e32 v205, v197
	v_mov_b32_e32 v222, 0x358637bd
	s_mov_b32 s69, 0x800000
	s_mov_b64 s[20:21], 0x100000
	s_mov_b32 s76, 0x100000
	s_mov_b64 s[22:23], 0x120000
	s_mov_b32 s77, 0x120000
	s_mov_b64 s[24:25], 0x140000
	s_mov_b32 s78, 0x140000
	s_mov_b64 s[26:27], 0x160000
	s_mov_b32 s79, 0x160000
	v_mov_b64_e32 v[206:207], 0x7ff
	v_add_u32_e32 v223, 0, v0
	s_barrier
	s_waitcnt vmcnt(0)
	s_branch .LBB0_1277

.LBB0_1284:
	s_ashr_i32 s31, s30, 31
	s_lshl_b64 s[36:37], s[30:31], 19
	s_add_u32 s36, s12, s36
	s_addc_u32 s37, s13, s37
	s_and_b64 s[40:41], s[38:39], exec
	s_cselect_b32 s31, s37, s47
	s_cselect_b32 s81, s36, s46
	s_ashr_i32 s29, s28, 31
	s_lshl_b64 s[40:41], s[28:29], 19
	s_add_u32 s40, s53, s40
	s_addc_u32 s41, s54, s41
	s_and_b64 s[48:49], s[38:39], exec
	s_cselect_b32 s29, s41, s45
	s_cselect_b32 s82, s40, s44
	v_lshl_add_u32 v208, s42, 8, v193
	s_add_u32 s42, s46, 0x40080
	s_addc_u32 s43, s47, 0
	v_ashrrev_i32_e32 v209, 31, v208
	s_add_u32 s83, s44, 0x100
	v_mov_b32_e32 v0, 0
	v_lshl_add_u64 v[210:211], v[208:209], 2, s[6:7]
	s_addc_u32 s84, s45, 0
	s_mov_b32 s85, -2
	v_mov_b32_e32 v1, v0
	v_mov_b32_e32 v2, v0
	v_mov_b32_e32 v3, v0
	v_mov_b32_e32 v4, v0
	v_mov_b32_e32 v5, v0
	v_mov_b32_e32 v6, v0
	v_mov_b32_e32 v7, v0
	v_mov_b32_e32 v16, v0
	v_mov_b32_e32 v17, v0
	v_mov_b32_e32 v18, v0
	v_mov_b32_e32 v19, v0
	v_mov_b32_e32 v20, v0
	v_mov_b32_e32 v21, v0
	v_mov_b32_e32 v22, v0
	v_mov_b32_e32 v23, v0
	v_mov_b32_e32 v32, v0
	v_mov_b32_e32 v33, v0
	v_mov_b32_e32 v34, v0
	v_mov_b32_e32 v35, v0
	v_mov_b32_e32 v36, v0
	v_mov_b32_e32 v37, v0
	v_mov_b32_e32 v38, v0
	v_mov_b32_e32 v39, v0
	v_mov_b32_e32 v48, v0
	v_mov_b32_e32 v49, v0
	v_mov_b32_e32 v50, v0
	v_mov_b32_e32 v51, v0
	v_mov_b32_e32 v52, v0
	v_mov_b32_e32 v53, v0
	v_mov_b32_e32 v54, v0
	v_mov_b32_e32 v55, v0
	v_mov_b32_e32 v8, v0
	v_mov_b32_e32 v9, v0
	v_mov_b32_e32 v10, v0
	v_mov_b32_e32 v11, v0
	v_mov_b32_e32 v12, v0
	v_mov_b32_e32 v13, v0
	v_mov_b32_e32 v14, v0
	v_mov_b32_e32 v15, v0
	v_mov_b32_e32 v24, v0
	v_mov_b32_e32 v25, v0
	v_mov_b32_e32 v26, v0
	v_mov_b32_e32 v27, v0
	v_mov_b32_e32 v28, v0
	v_mov_b32_e32 v29, v0
	v_mov_b32_e32 v30, v0
	v_mov_b32_e32 v31, v0
	v_mov_b32_e32 v40, v0
	v_mov_b32_e32 v41, v0
	v_mov_b32_e32 v42, v0
	v_mov_b32_e32 v43, v0
	v_mov_b32_e32 v44, v0
	v_mov_b32_e32 v45, v0
	v_mov_b32_e32 v46, v0
	v_mov_b32_e32 v47, v0
	v_mov_b32_e32 v56, v0
	v_mov_b32_e32 v57, v0
	v_mov_b32_e32 v58, v0
	v_mov_b32_e32 v59, v0
	v_mov_b32_e32 v60, v0
	v_mov_b32_e32 v61, v0
	v_mov_b32_e32 v62, v0
	v_mov_b32_e32 v63, v0
	v_mov_b32_e32 v64, v0
	v_mov_b32_e32 v65, v0
	v_mov_b32_e32 v66, v0
	v_mov_b32_e32 v67, v0
	v_mov_b32_e32 v68, v0
	v_mov_b32_e32 v69, v0
	v_mov_b32_e32 v70, v0
	v_mov_b32_e32 v71, v0
	v_mov_b32_e32 v80, v0
	v_mov_b32_e32 v81, v0
	v_mov_b32_e32 v82, v0
	v_mov_b32_e32 v83, v0
	v_mov_b32_e32 v84, v0
	v_mov_b32_e32 v85, v0
	v_mov_b32_e32 v86, v0
	v_mov_b32_e32 v87, v0
	v_mov_b32_e32 v96, v0
	v_mov_b32_e32 v97, v0
	v_mov_b32_e32 v98, v0
	v_mov_b32_e32 v99, v0
	v_mov_b32_e32 v100, v0
	v_mov_b32_e32 v101, v0
	v_mov_b32_e32 v102, v0
	v_mov_b32_e32 v103, v0
	v_mov_b32_e32 v112, v0
	v_mov_b32_e32 v113, v0
	v_mov_b32_e32 v114, v0
	v_mov_b32_e32 v115, v0
	v_mov_b32_e32 v116, v0
	v_mov_b32_e32 v117, v0
	v_mov_b32_e32 v118, v0
	v_mov_b32_e32 v119, v0
	v_mov_b32_e32 v72, v0
	v_mov_b32_e32 v73, v0
	v_mov_b32_e32 v74, v0
	v_mov_b32_e32 v75, v0
	v_mov_b32_e32 v76, v0
	v_mov_b32_e32 v77, v0
	v_mov_b32_e32 v78, v0
	v_mov_b32_e32 v79, v0
	v_mov_b32_e32 v88, v0
	v_mov_b32_e32 v89, v0
	v_mov_b32_e32 v90, v0
	v_mov_b32_e32 v91, v0
	v_mov_b32_e32 v92, v0
	v_mov_b32_e32 v93, v0
	v_mov_b32_e32 v94, v0
	v_mov_b32_e32 v95, v0
	v_mov_b32_e32 v104, v0
	v_mov_b32_e32 v105, v0
	v_mov_b32_e32 v106, v0
	v_mov_b32_e32 v107, v0
	v_mov_b32_e32 v108, v0
	v_mov_b32_e32 v109, v0
	v_mov_b32_e32 v110, v0
	v_mov_b32_e32 v111, v0
	v_mov_b32_e32 v120, v0
	v_mov_b32_e32 v121, v0
	v_mov_b32_e32 v122, v0
	v_mov_b32_e32 v123, v0
	v_mov_b32_e32 v124, v0
	v_mov_b32_e32 v125, v0
	v_mov_b32_e32 v126, v0
	v_mov_b32_e32 v127, v0
	s_branch .LBB0_1286

.LBB0_1288:
	v_add_u32_e32 v128, 0, v220
	v_add_u32_e32 v129, 0x10000, v128
	v_add_u32_e32 v140, 0x14000, v128
	ds_read_b128 v[144:147], v129
	ds_read_b128 v[148:151], v129 offset:1024
	ds_read_b128 v[152:155], v129 offset:2048
	ds_read_b128 v[156:159], v129 offset:3072
	ds_read_b128 v[128:131], v140
	ds_read_b128 v[132:135], v140 offset:1024
	ds_read_b128 v[136:139], v140 offset:2048
	ds_read_b128 v[140:143], v140 offset:3072
	v_lshl_add_u64 v[212:213], s[42:43], 0, v[202:203]
	s_add_i32 m0, s56, 0xc000
	ds_read_b128 v[184:187], v223
	ds_read_b128 v[188:191], v223 offset:1024
	ds_read_b128 v[176:179], v223 offset:2048
	ds_read_b128 v[180:183], v223 offset:3072
	ds_read_b128 v[168:171], v223 offset:4096
	ds_read_b128 v[172:175], v223 offset:5120
	ds_read_b128 v[160:163], v223 offset:6144
	ds_read_b128 v[164:167], v223 offset:7168
	global_load_lds_dwordx4 v[212:213], off
	v_lshl_add_u64 v[212:213], s[42:43], 0, v[204:205]
	s_add_i32 m0, s56, 0xe000
	s_mov_b64 s[48:49], -1
	global_load_lds_dwordx4 v[212:213], off
	s_cmp_eq_i32 s85, -2
	s_cbranch_scc1 .LBB0_1292
	s_and_b64 vcc, exec, s[46:47]
	s_cbranch_vccz .LBB0_1290
	s_waitcnt vmcnt(8)
	s_mov_b64 s[48:49], 0

.LBB0_1292:
	s_add_u32 s48, s42, 0xfffc0080
	s_addc_u32 s49, s43, -1
	s_waitcnt lgkmcnt(0)
	s_and_b64 s[44:45], s[44:45], exec
	s_cselect_b32 s49, s31, s49
	s_cselect_b32 s48, s81, s48
	s_cselect_b32 s45, s29, s84
	s_cselect_b32 s44, s82, s83
	s_barrier
	s_waitcnt lgkmcnt(0)
	v_mfma_f32_16x16x32_bf16 v[124:127], v[144:147], v[184:187], v[124:127]
	v_mfma_f32_16x16x32_bf16 v[120:123], v[152:155], v[184:187], v[120:123]
	v_mfma_f32_16x16x32_bf16 v[108:111], v[144:147], v[176:179], v[108:111]
	v_mfma_f32_16x16x32_bf16 v[104:107], v[152:155], v[176:179], v[104:107]
	v_mfma_f32_16x16x32_bf16 v[92:95], v[144:147], v[168:171], v[92:95]
	v_mfma_f32_16x16x32_bf16 v[88:91], v[152:155], v[168:171], v[88:91]
	v_mfma_f32_16x16x32_bf16 v[76:79], v[144:147], v[160:163], v[76:79]
	v_mfma_f32_16x16x32_bf16 v[72:75], v[152:155], v[160:163], v[72:75]
	v_mfma_f32_16x16x32_bf16 v[124:127], v[148:151], v[188:191], v[124:127]
	v_mfma_f32_16x16x32_bf16 v[120:123], v[156:159], v[188:191], v[120:123]
	v_mfma_f32_16x16x32_bf16 v[108:111], v[148:151], v[180:183], v[108:111]
	v_mfma_f32_16x16x32_bf16 v[104:107], v[156:159], v[180:183], v[104:107]
	v_mfma_f32_16x16x32_bf16 v[92:95], v[148:151], v[172:175], v[92:95]
	v_mfma_f32_16x16x32_bf16 v[88:91], v[156:159], v[172:175], v[88:91]
	v_mfma_f32_16x16x32_bf16 v[76:79], v[148:151], v[164:167], v[76:79]
	v_mfma_f32_16x16x32_bf16 v[72:75], v[156:159], v[164:167], v[72:75]
	v_mfma_f32_16x16x32_bf16 v[116:119], v[128:131], v[184:187], v[116:119]
	v_mfma_f32_16x16x32_bf16 v[112:115], v[136:139], v[184:187], v[112:115]
	v_mfma_f32_16x16x32_bf16 v[100:103], v[128:131], v[176:179], v[100:103]
	v_mfma_f32_16x16x32_bf16 v[96:99], v[136:139], v[176:179], v[96:99]
	v_mfma_f32_16x16x32_bf16 v[84:87], v[128:131], v[168:171], v[84:87]
	v_mfma_f32_16x16x32_bf16 v[80:83], v[136:139], v[168:171], v[80:83]
	v_mfma_f32_16x16x32_bf16 v[68:71], v[128:131], v[160:163], v[68:71]
	v_mfma_f32_16x16x32_bf16 v[64:67], v[136:139], v[160:163], v[64:67]
	v_mfma_f32_16x16x32_bf16 v[116:119], v[132:135], v[188:191], v[116:119]
	v_mfma_f32_16x16x32_bf16 v[112:115], v[140:143], v[188:191], v[112:115]
	v_mfma_f32_16x16x32_bf16 v[100:103], v[132:135], v[180:183], v[100:103]
	v_mfma_f32_16x16x32_bf16 v[96:99], v[140:143], v[180:183], v[96:99]
	v_mfma_f32_16x16x32_bf16 v[84:87], v[132:135], v[172:175], v[84:87]
	v_mfma_f32_16x16x32_bf16 v[80:83], v[140:143], v[172:175], v[80:83]
	v_mfma_f32_16x16x32_bf16 v[68:71], v[132:135], v[164:167], v[68:71]
	v_mfma_f32_16x16x32_bf16 v[64:67], v[140:143], v[164:167], v[64:67]
	s_barrier
	s_mov_b32 m0, s57
	v_lshl_add_u64 v[218:219], s[44:45], 0, v[196:197]
	s_add_u32 s50, s44, 0x40000
	ds_read_b128 v[184:187], v223 offset:16384
	ds_read_b128 v[188:191], v223 offset:17408
	ds_read_b128 v[176:179], v223 offset:18432
	ds_read_b128 v[180:183], v223 offset:19456
	ds_read_b128 v[168:171], v223 offset:20480
	ds_read_b128 v[172:175], v223 offset:21504
	ds_read_b128 v[160:163], v223 offset:22528
	ds_read_b128 v[164:167], v223 offset:23552
	global_load_lds_dwordx4 v[218:219], off
	v_lshl_add_u64 v[216:217], s[44:45], 0, v[200:201]
	s_mov_b32 m0, s58
	s_addc_u32 s51, s45, 0
	global_load_lds_dwordx4 v[216:217], off
	v_lshl_add_u64 v[212:213], s[50:51], 0, v[196:197]
	s_mov_b32 m0, s59
	v_lshl_add_u64 v[214:215], s[48:49], 0, v[198:199]
	global_load_lds_dwordx4 v[212:213], off
	v_lshl_add_u64 v[212:213], s[50:51], 0, v[200:201]
	s_mov_b32 m0, s60
	s_mov_b64 s[50:51], -1
	global_load_lds_dwordx4 v[212:213], off
	v_lshl_add_u64 v[212:213], s[48:49], 0, v[194:195]
	s_mov_b32 m0, s56
	s_and_b64 vcc, exec, s[46:47]
	global_load_lds_dwordx4 v[212:213], off
	s_mov_b32 m0, s61
	s_nop 0
	global_load_lds_dwordx4 v[214:215], off
	s_cmp_eq_i32 s85, -2
	s_cbranch_scc1 .LBB0_1285
	s_cbranch_vccz .LBB0_1294
	s_waitcnt vmcnt(8)
	s_mov_b64 s[50:51], 0

.LBB0_1496:
	s_add_u32 s4, s72, 0x48e0000
	s_addc_u32 s5, s73, 0
	s_lshl_b32 s6, s6, 5
	s_and_b32 s18, s6, 0x60
	s_mov_b64 s[6:7], 0x80
	s_add_i32 m0, s48, 0x18000
	v_lshl_add_u64 v[6:7], v[6:7], 0, s[6:7]
	s_lshl_b32 s11, s10, 13
	s_lshl_b32 s19, s18, 7
	s_waitcnt vmcnt(2)
	s_barrier
	global_load_lds_dwordx4 v[6:7], off
	v_lshl_add_u64 v[4:5], v[4:5], 0, s[6:7]
	s_add_i32 m0, s48, 0x1a000
	s_add_i32 s57, s48, 0x8000
	s_add_i32 s58, s48, 0xa000
	global_load_lds_dwordx4 v[4:5], off
	v_lshl_add_u64 v[0:1], v[0:1], 0, s[6:7]
	s_mov_b32 m0, s57
	s_add_u32 s16, s38, 0x40080
	global_load_lds_dwordx4 v[0:1], off
	v_lshl_add_u64 v[0:1], v[2:3], 0, s[6:7]
	s_mov_b32 m0, s58
	s_addc_u32 s17, s39, 0
	global_load_lds_dwordx4 v[0:1], off
	s_add_i32 m0, s48, 0x1c000
	v_lshl_add_u64 v[0:1], s[16:17], 0, v[196:197]
	global_load_lds_dwordx4 v[0:1], off
	v_lshl_add_u64 v[0:1], s[16:17], 0, v[200:201]
	s_add_i32 m0, s48, 0x1e000
	s_sext_i32_i8 s61, s8
	global_load_lds_dwordx4 v[0:1], off
	v_and_b32_e32 v0, 15, v192
	v_lshlrev_b32_e32 v1, 1, v11
	v_lshlrev_b32_e32 v2, 2, v192
	v_lshlrev_b32_e32 v3, 6, v192
	s_movk_i32 s8, 0x3c0
	v_lshl_or_b32 v218, s10, 6, v0
	v_lshl_or_b32 v0, v0, 6, v1
	v_and_b32_e32 v2, 32, v2
	v_and_or_b32 v1, v3, s8, v1
	v_bitop3_b32 v219, s19, v1, v2 bitop3:0xf6
	v_lshlrev_b32_e32 v1, 8, v192
	v_bitop3_b32 v0, v0, s11, v2 bitop3:0xde
	v_and_b32_e32 v1, 0x38000, v1
	v_lshlrev_b32_e32 v2, 11, v10
	v_or3_b32 v1, v8, v1, v2
	v_add_u32_e32 v192, v1, v9
	v_lshlrev_b32_e32 v1, 4, v12
	s_waitcnt vmcnt(6)
	v_and_b32_e32 v1, 0x78000, v1
	s_cmpk_lt_u32 s9, 0x100
	v_or3_b32 v1, v8, v1, v2
	s_cselect_b64 s[8:9], -1, 0
	s_ashr_i32 s59, s34, 31
	v_or_b32_e32 v220, s18, v11
	v_mov_b32_e32 v193, v197
	v_add_u32_e32 v202, v1, v9
	v_mov_b32_e32 v203, v197
	v_mov_b32_e32 v221, 0x358637bd
	s_mov_b32 s60, 0x800000
	s_mov_b64 s[10:11], 0x20000
	s_mov_b64 s[16:17], 0x24000
	s_mov_b64 s[18:19], 0x28000
	s_mov_b64 s[20:21], 0x2c000
	v_mov_b64_e32 v[204:205], 0x1ff
	v_add_u32_e32 v222, 0, v0
	s_barrier
	s_waitcnt vmcnt(0)
	s_branch .LBB0_1499

.LBB0_1506:
	s_ashr_i32 s25, s24, 31
	s_lshl_b64 s[26:27], s[24:25], 19
	s_add_u32 s26, s12, s26
	s_addc_u32 s27, s13, s27
	s_and_b64 s[30:31], s[28:29], exec
	s_cselect_b32 s25, s27, s41
	s_cselect_b32 s62, s26, s40
	s_ashr_i32 s23, s22, 31
	s_lshl_b64 s[30:31], s[22:23], 19
	s_add_u32 s30, s35, s30
	s_addc_u32 s31, s46, s31
	s_and_b64 s[42:43], s[28:29], exec
	s_cselect_b32 s23, s31, s39
	s_cselect_b32 s63, s30, s38
	v_lshl_add_u32 v206, s36, 8, v218
	s_add_u32 s36, s40, 0x40080
	s_addc_u32 s37, s41, 0
	v_ashrrev_i32_e32 v207, 31, v206
	s_add_u32 s64, s38, 0x100
	v_mov_b32_e32 v0, 0
	v_lshl_add_u64 v[208:209], v[206:207], 2, s[4:5]
	s_addc_u32 s65, s39, 0
	s_mov_b32 s66, -2
	v_mov_b32_e32 v1, v0
	v_mov_b32_e32 v2, v0
	v_mov_b32_e32 v3, v0
	v_mov_b32_e32 v4, v0
	v_mov_b32_e32 v5, v0
	v_mov_b32_e32 v6, v0
	v_mov_b32_e32 v7, v0
	v_mov_b32_e32 v16, v0
	v_mov_b32_e32 v17, v0
	v_mov_b32_e32 v18, v0
	v_mov_b32_e32 v19, v0
	v_mov_b32_e32 v20, v0
	v_mov_b32_e32 v21, v0
	v_mov_b32_e32 v22, v0
	v_mov_b32_e32 v23, v0
	v_mov_b32_e32 v32, v0
	v_mov_b32_e32 v33, v0
	v_mov_b32_e32 v34, v0
	v_mov_b32_e32 v35, v0
	v_mov_b32_e32 v36, v0
	v_mov_b32_e32 v37, v0
	v_mov_b32_e32 v38, v0
	v_mov_b32_e32 v39, v0
	v_mov_b32_e32 v48, v0
	v_mov_b32_e32 v49, v0
	v_mov_b32_e32 v50, v0
	v_mov_b32_e32 v51, v0
	v_mov_b32_e32 v52, v0
	v_mov_b32_e32 v53, v0
	v_mov_b32_e32 v54, v0
	v_mov_b32_e32 v55, v0
	v_mov_b32_e32 v8, v0
	v_mov_b32_e32 v9, v0
	v_mov_b32_e32 v10, v0
	v_mov_b32_e32 v11, v0
	v_mov_b32_e32 v12, v0
	v_mov_b32_e32 v13, v0
	v_mov_b32_e32 v14, v0
	v_mov_b32_e32 v15, v0
	v_mov_b32_e32 v24, v0
	v_mov_b32_e32 v25, v0
	v_mov_b32_e32 v26, v0
	v_mov_b32_e32 v27, v0
	v_mov_b32_e32 v28, v0
	v_mov_b32_e32 v29, v0
	v_mov_b32_e32 v30, v0
	v_mov_b32_e32 v31, v0
	v_mov_b32_e32 v40, v0
	v_mov_b32_e32 v41, v0
	v_mov_b32_e32 v42, v0
	v_mov_b32_e32 v43, v0
	v_mov_b32_e32 v44, v0
	v_mov_b32_e32 v45, v0
	v_mov_b32_e32 v46, v0
	v_mov_b32_e32 v47, v0
	v_mov_b32_e32 v56, v0
	v_mov_b32_e32 v57, v0
	v_mov_b32_e32 v58, v0
	v_mov_b32_e32 v59, v0
	v_mov_b32_e32 v60, v0
	v_mov_b32_e32 v61, v0
	v_mov_b32_e32 v62, v0
	v_mov_b32_e32 v63, v0
	v_mov_b32_e32 v64, v0
	v_mov_b32_e32 v65, v0
	v_mov_b32_e32 v66, v0
	v_mov_b32_e32 v67, v0
	v_mov_b32_e32 v68, v0
	v_mov_b32_e32 v69, v0
	v_mov_b32_e32 v70, v0
	v_mov_b32_e32 v71, v0
	v_mov_b32_e32 v80, v0
	v_mov_b32_e32 v81, v0
	v_mov_b32_e32 v82, v0
	v_mov_b32_e32 v83, v0
	v_mov_b32_e32 v84, v0
	v_mov_b32_e32 v85, v0
	v_mov_b32_e32 v86, v0
	v_mov_b32_e32 v87, v0
	v_mov_b32_e32 v96, v0
	v_mov_b32_e32 v97, v0
	v_mov_b32_e32 v98, v0
	v_mov_b32_e32 v99, v0
	v_mov_b32_e32 v100, v0
	v_mov_b32_e32 v101, v0
	v_mov_b32_e32 v102, v0
	v_mov_b32_e32 v103, v0
	v_mov_b32_e32 v112, v0
	v_mov_b32_e32 v113, v0
	v_mov_b32_e32 v114, v0
	v_mov_b32_e32 v115, v0
	v_mov_b32_e32 v116, v0
	v_mov_b32_e32 v117, v0
	v_mov_b32_e32 v118, v0
	v_mov_b32_e32 v119, v0
	v_mov_b32_e32 v72, v0
	v_mov_b32_e32 v73, v0
	v_mov_b32_e32 v74, v0
	v_mov_b32_e32 v75, v0
	v_mov_b32_e32 v76, v0
	v_mov_b32_e32 v77, v0
	v_mov_b32_e32 v78, v0
	v_mov_b32_e32 v79, v0
	v_mov_b32_e32 v88, v0
	v_mov_b32_e32 v89, v0
	v_mov_b32_e32 v90, v0
	v_mov_b32_e32 v91, v0
	v_mov_b32_e32 v92, v0
	v_mov_b32_e32 v93, v0
	v_mov_b32_e32 v94, v0
	v_mov_b32_e32 v95, v0
	v_mov_b32_e32 v104, v0
	v_mov_b32_e32 v105, v0
	v_mov_b32_e32 v106, v0
	v_mov_b32_e32 v107, v0
	v_mov_b32_e32 v108, v0
	v_mov_b32_e32 v109, v0
	v_mov_b32_e32 v110, v0
	v_mov_b32_e32 v111, v0
	v_mov_b32_e32 v120, v0
	v_mov_b32_e32 v121, v0
	v_mov_b32_e32 v122, v0
	v_mov_b32_e32 v123, v0
	v_mov_b32_e32 v132, v0
	v_mov_b32_e32 v133, v0
	v_mov_b32_e32 v134, v0
	v_mov_b32_e32 v135, v0
	s_branch .LBB0_1508

.LBB0_1510:
	v_add_u32_e32 v124, 0, v219
	v_add_u32_e32 v125, 0x10000, v124
	v_add_u32_e32 v140, 0x14000, v124
	ds_read_b128 v[144:147], v125
	ds_read_b128 v[148:151], v125 offset:1024
	ds_read_b128 v[152:155], v125 offset:2048
	ds_read_b128 v[156:159], v125 offset:3072
	ds_read_b128 v[124:127], v140
	ds_read_b128 v[128:131], v140 offset:1024
	ds_read_b128 v[136:139], v140 offset:2048
	ds_read_b128 v[140:143], v140 offset:3072
	v_lshl_add_u64 v[210:211], s[36:37], 0, v[192:193]
	s_add_i32 m0, s48, 0xc000
	ds_read_b128 v[184:187], v222
	ds_read_b128 v[188:191], v222 offset:1024
	ds_read_b128 v[176:179], v222 offset:2048
	ds_read_b128 v[180:183], v222 offset:3072
	ds_read_b128 v[168:171], v222 offset:4096
	ds_read_b128 v[172:175], v222 offset:5120
	ds_read_b128 v[160:163], v222 offset:6144
	ds_read_b128 v[164:167], v222 offset:7168
	global_load_lds_dwordx4 v[210:211], off
	v_lshl_add_u64 v[210:211], s[36:37], 0, v[202:203]
	s_add_i32 m0, s48, 0xe000
	s_mov_b64 s[42:43], -1
	global_load_lds_dwordx4 v[210:211], off
	s_cmp_eq_i32 s66, -2
	s_cbranch_scc1 .LBB0_1514
	s_and_b64 vcc, exec, s[40:41]
	s_cbranch_vccz .LBB0_1512
	s_waitcnt vmcnt(8)
	s_mov_b64 s[42:43], 0

.LBB0_1514:
	s_add_u32 s42, s36, 0xfffc0080
	s_addc_u32 s43, s37, -1
	s_waitcnt lgkmcnt(0)
	s_and_b64 s[38:39], s[38:39], exec
	s_cselect_b32 s43, s25, s43
	s_cselect_b32 s42, s62, s42
	s_cselect_b32 s39, s23, s65
	s_cselect_b32 s38, s63, s64
	s_barrier
	s_waitcnt lgkmcnt(0)
	v_mfma_f32_16x16x32_bf16 v[132:135], v[144:147], v[184:187], v[132:135]
	v_mfma_f32_16x16x32_bf16 v[120:123], v[152:155], v[184:187], v[120:123]
	v_mfma_f32_16x16x32_bf16 v[108:111], v[144:147], v[176:179], v[108:111]
	v_mfma_f32_16x16x32_bf16 v[104:107], v[152:155], v[176:179], v[104:107]
	v_mfma_f32_16x16x32_bf16 v[92:95], v[144:147], v[168:171], v[92:95]
	v_mfma_f32_16x16x32_bf16 v[88:91], v[152:155], v[168:171], v[88:91]
	v_mfma_f32_16x16x32_bf16 v[76:79], v[144:147], v[160:163], v[76:79]
	v_mfma_f32_16x16x32_bf16 v[72:75], v[152:155], v[160:163], v[72:75]
	v_mfma_f32_16x16x32_bf16 v[132:135], v[148:151], v[188:191], v[132:135]
	v_mfma_f32_16x16x32_bf16 v[120:123], v[156:159], v[188:191], v[120:123]
	v_mfma_f32_16x16x32_bf16 v[108:111], v[148:151], v[180:183], v[108:111]
	v_mfma_f32_16x16x32_bf16 v[104:107], v[156:159], v[180:183], v[104:107]
	v_mfma_f32_16x16x32_bf16 v[92:95], v[148:151], v[172:175], v[92:95]
	v_mfma_f32_16x16x32_bf16 v[88:91], v[156:159], v[172:175], v[88:91]
	v_mfma_f32_16x16x32_bf16 v[76:79], v[148:151], v[164:167], v[76:79]
	v_mfma_f32_16x16x32_bf16 v[72:75], v[156:159], v[164:167], v[72:75]
	v_mfma_f32_16x16x32_bf16 v[116:119], v[124:127], v[184:187], v[116:119]
	v_mfma_f32_16x16x32_bf16 v[112:115], v[136:139], v[184:187], v[112:115]
	v_mfma_f32_16x16x32_bf16 v[100:103], v[124:127], v[176:179], v[100:103]
	v_mfma_f32_16x16x32_bf16 v[96:99], v[136:139], v[176:179], v[96:99]
	v_mfma_f32_16x16x32_bf16 v[84:87], v[124:127], v[168:171], v[84:87]
	v_mfma_f32_16x16x32_bf16 v[80:83], v[136:139], v[168:171], v[80:83]
	v_mfma_f32_16x16x32_bf16 v[68:71], v[124:127], v[160:163], v[68:71]
	v_mfma_f32_16x16x32_bf16 v[64:67], v[136:139], v[160:163], v[64:67]
	v_mfma_f32_16x16x32_bf16 v[116:119], v[128:131], v[188:191], v[116:119]
	v_mfma_f32_16x16x32_bf16 v[112:115], v[140:143], v[188:191], v[112:115]
	v_mfma_f32_16x16x32_bf16 v[100:103], v[128:131], v[180:183], v[100:103]
	v_mfma_f32_16x16x32_bf16 v[96:99], v[140:143], v[180:183], v[96:99]
	v_mfma_f32_16x16x32_bf16 v[84:87], v[128:131], v[172:175], v[84:87]
	v_mfma_f32_16x16x32_bf16 v[80:83], v[140:143], v[172:175], v[80:83]
	v_mfma_f32_16x16x32_bf16 v[68:71], v[128:131], v[164:167], v[68:71]
	v_mfma_f32_16x16x32_bf16 v[64:67], v[140:143], v[164:167], v[64:67]
	s_barrier
	s_mov_b32 m0, s49
	v_lshl_add_u64 v[216:217], s[38:39], 0, v[196:197]
	s_add_u32 s44, s38, 0x40000
	ds_read_b128 v[184:187], v222 offset:16384
	ds_read_b128 v[188:191], v222 offset:17408
	ds_read_b128 v[176:179], v222 offset:18432
	ds_read_b128 v[180:183], v222 offset:19456
	ds_read_b128 v[168:171], v222 offset:20480
	ds_read_b128 v[172:175], v222 offset:21504
	ds_read_b128 v[160:163], v222 offset:22528
	ds_read_b128 v[164:167], v222 offset:23552
	global_load_lds_dwordx4 v[216:217], off
	v_lshl_add_u64 v[214:215], s[38:39], 0, v[200:201]
	s_mov_b32 m0, s50
	s_addc_u32 s45, s39, 0
	global_load_lds_dwordx4 v[214:215], off
	v_lshl_add_u64 v[210:211], s[44:45], 0, v[196:197]
	s_mov_b32 m0, s51
	v_lshl_add_u64 v[212:213], s[42:43], 0, v[198:199]
	global_load_lds_dwordx4 v[210:211], off
	v_lshl_add_u64 v[210:211], s[44:45], 0, v[200:201]
	s_mov_b32 m0, s52
	s_mov_b64 s[44:45], -1
	global_load_lds_dwordx4 v[210:211], off
	v_lshl_add_u64 v[210:211], s[42:43], 0, v[194:195]
	s_mov_b32 m0, s48
	s_and_b64 vcc, exec, s[40:41]
	global_load_lds_dwordx4 v[210:211], off
	s_mov_b32 m0, s53
	s_nop 0
	global_load_lds_dwordx4 v[212:213], off
	s_cmp_eq_i32 s66, -2
	s_cbranch_scc1 .LBB0_1507
	s_cbranch_vccz .LBB0_1516
	s_waitcnt vmcnt(8)
	s_mov_b64 s[44:45], 0
